# post phase: tasks spread over all CUs (task = wave*G + bid, as gg_phase does) instead of 8 per CU on 88 CUs
# speedup vs baseline: 1.0239x; 1.0190x over previous
; __device__ __forceinline__ void post_phase(const Ctx& c, ArgsP a, int l) {
;     ...
;     for (int task = c.gw; task < 512 + 192; task += c.NGW) {
;         if (task < 512) {
;             const int bh = task >> 5, ch = task & 31, b = bh >> 2, hh = bh & 3, k = c.lane;
;             float up[16];
; #pragma unroll
;             for (int r = 0; r < 16; ++r) up[r] = gate_up[r * 256 + hh * 64 + k];
;             const float bias = gate_b[hh * 64 + k];
;             float cum = 0.f;
;             const int tok0 = b * SEQ + ch * 64; const size_t rb = (size_t)bh * SEQ + ch * 64;
.LBB0_220:
	s_and_b64 vcc, exec, s[4:5]
	s_cbranch_vccz .LBB0_234
	v_readlane_b32 s66, v254, 62
	s_nop 3
	s_mul_i32 s66, s66, s93
	s_add_i32 s66, s66, s76
	s_cmpk_gt_i32 s66, 0x2bf
	s_cbranch_scc1 .LBB0_234
	s_add_u32 s77, s48, 0x2a700000
	s_addc_u32 s8, s49, 0
	v_writelane_b32 v255, s67, 22
	s_load_dwordx4 s[4:7], s[0:1], 0x38
	s_add_u32 s2, s48, 0x2ab00000
	v_lshrrev_b32_e32 v5, 5, v198
	v_writelane_b32 v255, s2, 12
	s_addc_u32 s2, s49, 0
	v_lshlrev_b32_e32 v2, 2, v198
	v_mov_b32_e32 v3, v1
	v_lshlrev_b32_e32 v7, 2, v5
	v_writelane_b32 v255, s2, 23
	s_add_u32 s2, s48, 0x2af00000
	v_lshl_add_u64 v[90:91], s[48:49], 0, v[2:3]
	v_and_b32_e32 v3, 31, v228
	v_or_b32_e32 v8, 2, v7
	v_writelane_b32 v255, s2, 24
	s_addc_u32 s2, s49, 0
	v_cmp_gt_u32_e64 s[10:11], v8, v3
	v_or_b32_e32 v8, 3, v7
	v_writelane_b32 v255, s2, 25
	v_readlane_b32 s2, v254, 39
	v_cmp_gt_u32_e64 s[12:13], v8, v3
	v_or_b32_e32 v8, 8, v7
	v_readlane_b32 s3, v254, 40
	s_waitcnt lgkmcnt(0)
	s_add_u32 s4, s4, s2
	v_cmp_gt_u32_e64 s[14:15], v8, v3
	v_or_b32_e32 v8, 9, v7
	s_addc_u32 s5, s5, s3
	v_readlane_b32 s2, v254, 41
	v_cmp_gt_u32_e64 s[16:17], v8, v3
	v_or_b32_e32 v8, 10, v7
	v_readlane_b32 s3, v254, 42
	s_add_u32 s2, s6, s2
	v_cmp_gt_u32_e64 s[18:19], v8, v3
	v_or_b32_e32 v8, 11, v7
	s_addc_u32 s3, s7, s3
	v_cmp_gt_u32_e64 s[20:21], v8, v3
	v_or_b32_e32 v8, 16, v7
	v_writelane_b32 v255, s2, 26
	v_cmp_gt_u32_e64 s[22:23], v8, v3
	v_or_b32_e32 v8, 17, v7
	v_writelane_b32 v255, s3, 27
	v_readlane_b32 s2, v254, 61
	v_cmp_gt_u32_e64 s[24:25], v8, v3
	v_or_b32_e32 v8, 18, v7
	s_lshr_b32 s40, s2, 6
	s_mov_b64 s[2:3], 0x2b400000
	v_cmp_gt_u32_e64 s[26:27], v8, v3
	v_or_b32_e32 v8, 19, v7
	v_lshl_add_u64 v[92:93], v[90:91], 0, s[2:3]
	s_mov_b64 s[2:3], 0x2b300000
	v_cmp_gt_u32_e64 s[28:29], v8, v3
	v_or_b32_e32 v8, 24, v7
	v_lshl_add_u64 v[96:97], v[90:91], 0, s[2:3]
	v_cmp_gt_u32_e64 s[2:3], v7, v3
	v_cmp_gt_u32_e64 s[30:31], v8, v3
	v_or_b32_e32 v8, 25, v7
	s_mov_b32 s7, s8
	v_writelane_b32 v255, s2, 28
	v_cmp_lt_u32_e64 s[8:9], v7, v3
	v_cmp_gt_u32_e64 s[34:35], v8, v3
	v_or_b32_e32 v8, 26, v7
	v_or_b32_e32 v7, 27, v7
	v_lshlrev_b32_e32 v2, 6, v3
	v_writelane_b32 v255, s3, 29
	v_cmp_gt_u32_e64 s[38:39], v7, v3
	v_readlane_b32 s2, v254, 63
	v_readlane_b32 s3, v254, 62
	v_lshlrev_b32_e32 v7, 4, v5
	s_ashr_i32 s67, s66, 31
	v_lshlrev_b32_e32 v4, 3, v5
	v_or_b32_e32 v6, 0x800, v2
	v_cmp_gt_u32_e64 s[36:37], v8, v3
	s_mov_b32 s92, s66
	s_lshl_b32 s2, s76, 11
	s_lshl_b32 s3, s3, 8
	v_lshl_or_b32 v100, v3, 9, v7
	s_lshl_b64 s[40:41], s[66:67], 15
	v_lshlrev_b32_e32 v5, 10, v5
	v_lshlrev_b32_e32 v3, 2, v3
	s_ashr_i32 s63, s62, 31
	v_lshlrev_b32_e32 v0, 1, v198
	v_lshlrev_b32_e32 v94, 7, v198
	v_mov_b32_e32 v95, v1
	s_add_i32 s89, s66, 0x600
	s_lshl_b32 s95, s66, 8
	s_lshl_b32 s3, s93, 11
	v_lshlrev_b32_e32 v98, 4, v198
	v_or3_b32 v102, s40, v5, v3
	v_mov_b32_e32 v103, s41
	s_lshl_b64 s[42:43], s[62:63], 15
	v_lshlrev_b32_e32 v104, 1, v2
	v_lshlrev_b32_e32 v106, 1, v4
	v_lshlrev_b32_e32 v108, 1, v6
	s_mov_b32 s63, s92
	s_mov_b32 s54, s66
	s_branch .LBB0_224
